# K-loop MFMA blocks: removed no-op lgkmcnt waits and redundant setprio 0/1 pairs, on top of the non-GEMM latency stack
# speedup vs baseline: 1.0137x; 1.0137x over previous
; #define PG8_STAGE(bufoff, gbase, voff) do { glds_s((const char*)(gbase), (voff), ldsb + (bufoff)); glds_s((const char*)(gbase) + rstep, (voff), ldsb + (bufoff) + 8192u); } while (0)
; #define PG8_LDA(dst, b, h) do { _Pragma("unroll") for (int m = 0; m < 4; ++m) _Pragma("unroll") for (int k = 0; k < 2; ++k) dst[m][k] = *(const LAS bf16x8*)(lds + PG8_SA(b, h) + aoff + m * 2048 + k * 1024); } while (0)
; #define PG8_LDB(dst, b, h) do { _Pragma("unroll") for (int n = 0; n < 2; ++n) _Pragma("unroll") for (int k = 0; k < 2; ++k) dst[n][k] = *(const LAS bf16x8*)(lds + PG8_SB(b, h) + boff + n * 2048 + k * 1024); } while (0)
; #define PG8_MMA(ai, bj, At, Bt) do { __builtin_amdgcn_s_setprio(1); _Pragma("unroll") for (int m = 0; m < 4; ++m) _Pragma("unroll") for (int n = 0; n < 2; ++n) _Pragma("unroll") for (int k = 0; k < 2; ++k) \
;         acc[ai][bj][m][n] = __builtin_amdgcn_mfma_f32_16x16x32_bf16(Bt[n][k], At[m][k], acc[ai][bj][m][n], 0, 0, 0); __builtin_amdgcn_s_setprio(0); } while (0)
; #define PG8_WAIT_V(n) asm volatile("s_waitcnt vmcnt(" #n ")" ::: "memory")
; #define PG8_WAIT_L(n) asm volatile("s_waitcnt lgkmcnt(" #n ")" ::: "memory")
; #define PG8_BAR __builtin_amdgcn_s_barrier()
; #define PG8_SCHED __builtin_amdgcn_sched_barrier(0)
; template <class Epi, class Sched>
; __device__ __forceinline__ void gemm_phase(LAS unsigned char* lds, const Gemm g, const Sched& S, const Epi& E, const int tid) {
;     ...
;             PG8_LDB(B0, 0, 0); PG8_LDB(B1, 0, 1); PG8_SCHED; PG8_LDA(At, 0, 0); if (!relax) PG8_STAGE(PG8_SA(1, 1), a1 + hstep, voffA);
;             if (relax) PG8_WAIT_V(16); else PG8_WAIT_V(8);
;             PG8_WAIT_L(0); PG8_BAR; PG8_MMA(0, 0, At, B0); PG8_MMA(0, 1, At, B1); PG8_BAR; PG8_SCHED;
;             PG8_LDA(At, 0, 1); PG8_STAGE(PG8_SB(0, 0), b2, voffB); PG8_STAGE(PG8_SB(0, 1), b2 + hstep, voffB); PG8_STAGE(PG8_SA(0, 0), a2, voffA);
;             if (relax) PG8_WAIT_V(16); else PG8_WAIT_V(8);
;             PG8_WAIT_L(0); PG8_BAR; PG8_MMA(1, 0, At, B0); PG8_MMA(1, 1, At, B1); PG8_BAR; PG8_SCHED;
.LBB0_193:
	s_add_u32 s8, s2, 0x100
	s_waitcnt lgkmcnt(0)
	s_addc_u32 s9, s3, 0
	s_add_u32 s44, s0, 0x100
	s_addc_u32 s45, s1, 0
	s_barrier
	s_setprio 1
	v_mfma_f32_16x16x32_bf16 v[0:3], v[80:83], v[36:39], 0
	v_mfma_f32_16x16x32_bf16 v[4:7], v[88:91], v[36:39], 0
	v_mfma_f32_16x16x32_bf16 v[8:11], v[80:83], v[44:47], 0
	v_mfma_f32_16x16x32_bf16 v[12:15], v[88:91], v[44:47], 0
	v_mfma_f32_16x16x32_bf16 v[16:19], v[80:83], v[52:55], 0
	v_mfma_f32_16x16x32_bf16 v[20:23], v[88:91], v[52:55], 0
	v_mfma_f32_16x16x32_bf16 v[24:27], v[80:83], v[60:63], 0
	v_mfma_f32_16x16x32_bf16 v[28:31], v[88:91], v[60:63], 0
	v_mfma_f32_16x16x32_bf16 v[0:3], v[84:87], v[40:43], v[0:3]
	v_mfma_f32_16x16x32_bf16 v[4:7], v[92:95], v[40:43], v[4:7]
	v_mfma_f32_16x16x32_bf16 v[8:11], v[84:87], v[48:51], v[8:11]
	v_mfma_f32_16x16x32_bf16 v[12:15], v[92:95], v[48:51], v[12:15]
	v_mfma_f32_16x16x32_bf16 v[16:19], v[84:87], v[56:59], v[16:19]
	v_mfma_f32_16x16x32_bf16 v[20:23], v[92:95], v[56:59], v[20:23]
	v_mfma_f32_16x16x32_bf16 v[24:27], v[84:87], v[96:99], v[24:27]
	v_mfma_f32_16x16x32_bf16 v[28:31], v[92:95], v[96:99], v[28:31]
	v_mfma_f32_16x16x32_bf16 v[32:35], v[64:67], v[36:39], 0
	v_mfma_f32_16x16x32_bf16 v[36:39], v[72:75], v[36:39], 0
	v_mfma_f32_16x16x32_bf16 v[32:35], v[68:71], v[40:43], v[32:35]
	v_mfma_f32_16x16x32_bf16 v[36:39], v[76:79], v[40:43], v[36:39]
	v_mfma_f32_16x16x32_bf16 v[40:43], v[64:67], v[44:47], 0
	v_mfma_f32_16x16x32_bf16 v[44:47], v[72:75], v[44:47], 0
	v_mfma_f32_16x16x32_bf16 v[40:43], v[68:71], v[48:51], v[40:43]
	v_mfma_f32_16x16x32_bf16 v[44:47], v[76:79], v[48:51], v[44:47]
	v_mfma_f32_16x16x32_bf16 v[48:51], v[64:67], v[52:55], 0
	v_mfma_f32_16x16x32_bf16 v[52:55], v[72:75], v[52:55], 0
	v_mfma_f32_16x16x32_bf16 v[48:51], v[68:71], v[56:59], v[48:51]
	v_mfma_f32_16x16x32_bf16 v[52:55], v[76:79], v[56:59], v[52:55]
	v_mfma_f32_16x16x32_bf16 v[56:59], v[64:67], v[60:63], 0
	v_mfma_f32_16x16x32_bf16 v[60:63], v[72:75], v[60:63], 0
	v_mfma_f32_16x16x32_bf16 v[56:59], v[68:71], v[96:99], v[56:59]
	v_mfma_f32_16x16x32_bf16 v[60:63], v[76:79], v[96:99], v[60:63]
	s_setprio 0
	s_barrier
	ds_read_b128 v[120:123], v250 offset:16384
	s_waitcnt vmcnt(35)
	ds_read_b128 v[124:127], v250 offset:17408
	ds_read_b128 v[112:115], v250 offset:18432
	ds_read_b128 v[116:119], v250 offset:19456
	ds_read_b128 v[104:107], v250 offset:20480
	ds_read_b128 v[108:111], v250 offset:21504
	ds_read_b128 v[96:99], v250 offset:22528
	ds_read_b128 v[100:103], v250 offset:23552
	s_mov_b32 m0, s50
	s_nop 0
	global_load_lds_dwordx4 v246, s[44:45]
	s_add_u32 s44, s44, s28
	s_addc_u32 s45, s45, s29
	s_add_u32 s85, s0, s30
	s_addc_u32 s96, s1, s31
	s_mov_b32 m0, s51
	s_nop 0
	global_load_lds_dwordx4 v246, s[44:45]
	s_add_u32 s44, s85, 0x100
	s_addc_u32 s45, s96, 0
	s_mov_b32 m0, s52
	s_nop 0
	global_load_lds_dwordx4 v246, s[44:45]
	s_add_u32 s44, s44, s28
	s_addc_u32 s45, s45, s29
	s_mov_b32 m0, s53
	s_nop 0
	global_load_lds_dwordx4 v246, s[44:45]
	s_nop 0
	s_mov_b32 m0, s49
	s_nop 0
	global_load_lds_dwordx4 v245, s[8:9]
	s_add_u32 s8, s8, s28
	s_addc_u32 s9, s9, s29
	s_mov_b32 m0, s54
	s_nop 0
	global_load_lds_dwordx4 v245, s[8:9]
	s_and_b64 vcc, exec, s[6:7]
	s_cbranch_vccz .LBB0_215
	s_waitcnt vmcnt(16)
	s_cbranch_execnz .LBB0_196

; #define PG8_STAGE(bufoff, gbase, voff) do { glds_s((const char*)(gbase), (voff), ldsb + (bufoff)); glds_s((const char*)(gbase) + rstep, (voff), ldsb + (bufoff) + 8192u); } while (0)
; #define PG8_LDA(dst, b, h) do { _Pragma("unroll") for (int m = 0; m < 4; ++m) _Pragma("unroll") for (int k = 0; k < 2; ++k) dst[m][k] = *(const LAS bf16x8*)(lds + PG8_SA(b, h) + aoff + m * 2048 + k * 1024); } while (0)
; #define PG8_LDB(dst, b, h) do { _Pragma("unroll") for (int n = 0; n < 2; ++n) _Pragma("unroll") for (int k = 0; k < 2; ++k) dst[n][k] = *(const LAS bf16x8*)(lds + PG8_SB(b, h) + boff + n * 2048 + k * 1024); } while (0)
; #define PG8_MMA(ai, bj, At, Bt) do { __builtin_amdgcn_s_setprio(1); _Pragma("unroll") for (int m = 0; m < 4; ++m) _Pragma("unroll") for (int n = 0; n < 2; ++n) _Pragma("unroll") for (int k = 0; k < 2; ++k) \
;         acc[ai][bj][m][n] = __builtin_amdgcn_mfma_f32_16x16x32_bf16(Bt[n][k], At[m][k], acc[ai][bj][m][n], 0, 0, 0); __builtin_amdgcn_s_setprio(0); } while (0)
; #define PG8_WAIT_V(n) asm volatile("s_waitcnt vmcnt(" #n ")" ::: "memory")
; #define PG8_WAIT_L(n) asm volatile("s_waitcnt lgkmcnt(" #n ")" ::: "memory")
; #define PG8_BAR __builtin_amdgcn_s_barrier()
; #define PG8_SCHED __builtin_amdgcn_sched_barrier(0)
; template <class Epi, class Sched>
; __device__ __forceinline__ void gemm_phase(LAS unsigned char* lds, const Gemm g, const Sched& S, const Epi& E, const int tid) {
;     ...
;             PG8_WAIT_L(0); PG8_BAR; PG8_MMA(0, 0, At, B0); PG8_MMA(0, 1, At, B1); PG8_BAR; PG8_SCHED;
;             PG8_LDA(At, 0, 1); PG8_STAGE(PG8_SB(0, 0), b2, voffB); PG8_STAGE(PG8_SB(0, 1), b2 + hstep, voffB); PG8_STAGE(PG8_SA(0, 0), a2, voffA);
;             if (relax) PG8_WAIT_V(16); else PG8_WAIT_V(8);
;             PG8_WAIT_L(0); PG8_BAR; PG8_MMA(1, 0, At, B0); PG8_MMA(1, 1, At, B1); PG8_BAR; PG8_SCHED;
;             PG8_LDB(B0, 1, 0); PG8_LDB(B1, 1, 1); PG8_SCHED; PG8_LDA(At, 1, 0); PG8_STAGE(PG8_SA(0, 1), a2 + hstep, voffA);
.LBB0_196:
	s_waitcnt lgkmcnt(0)
	s_barrier
	s_setprio 1
	s_waitcnt vmcnt(34) lgkmcnt(7)
	v_mfma_f32_16x16x32_bf16 v[128:131], v[80:83], v[120:123], 0
	v_mfma_f32_16x16x32_bf16 v[150:153], v[84:87], v[124:127], v[128:131]
	v_mfma_f32_16x16x32_bf16 v[128:131], v[88:91], v[120:123], 0
	v_mfma_f32_16x16x32_bf16 v[154:157], v[92:95], v[124:127], v[128:131]
	v_mfma_f32_16x16x32_bf16 v[128:131], v[80:83], v[112:115], 0
	v_mfma_f32_16x16x32_bf16 v[158:161], v[84:87], v[116:119], v[128:131]
	v_mfma_f32_16x16x32_bf16 v[128:131], v[88:91], v[112:115], 0
	v_mfma_f32_16x16x32_bf16 v[162:165], v[92:95], v[116:119], v[128:131]
	v_mfma_f32_16x16x32_bf16 v[128:131], v[80:83], v[104:107], 0
	v_mfma_f32_16x16x32_bf16 v[80:83], v[80:83], v[96:99], 0
	v_mfma_f32_16x16x32_bf16 v[166:169], v[84:87], v[108:111], v[128:131]
	v_mfma_f32_16x16x32_bf16 v[128:131], v[88:91], v[104:107], 0
	v_mfma_f32_16x16x32_bf16 v[174:177], v[84:87], v[100:103], v[80:83]
	v_mfma_f32_16x16x32_bf16 v[80:83], v[88:91], v[96:99], 0
	v_mfma_f32_16x16x32_bf16 v[170:173], v[92:95], v[108:111], v[128:131]
	v_mfma_f32_16x16x32_bf16 v[86:89], v[92:95], v[100:103], v[80:83]
	v_mfma_f32_16x16x32_bf16 v[80:83], v[64:67], v[120:123], 0
	v_mfma_f32_16x16x32_bf16 v[178:181], v[68:71], v[124:127], v[80:83]
	v_mfma_f32_16x16x32_bf16 v[80:83], v[72:75], v[120:123], 0
	v_mfma_f32_16x16x32_bf16 v[182:185], v[76:79], v[124:127], v[80:83]
	v_mfma_f32_16x16x32_bf16 v[80:83], v[64:67], v[112:115], 0
	v_mfma_f32_16x16x32_bf16 v[186:189], v[68:71], v[116:119], v[80:83]
	v_mfma_f32_16x16x32_bf16 v[80:83], v[72:75], v[112:115], 0
	v_mfma_f32_16x16x32_bf16 v[190:193], v[76:79], v[116:119], v[80:83]
	v_mfma_f32_16x16x32_bf16 v[80:83], v[64:67], v[104:107], 0
	v_mfma_f32_16x16x32_bf16 v[64:67], v[64:67], v[96:99], 0
	v_mfma_f32_16x16x32_bf16 v[194:197], v[68:71], v[108:111], v[80:83]
	v_mfma_f32_16x16x32_bf16 v[80:83], v[72:75], v[104:107], 0
	v_mfma_f32_16x16x32_bf16 v[202:205], v[68:71], v[100:103], v[64:67]
	v_mfma_f32_16x16x32_bf16 v[64:67], v[72:75], v[96:99], 0
	v_mfma_f32_16x16x32_bf16 v[198:201], v[76:79], v[108:111], v[80:83]
	v_mfma_f32_16x16x32_bf16 v[206:209], v[76:79], v[100:103], v[64:67]
	s_setprio 0
	s_barrier
	v_add_u32_e32 v252, 0x18000, v249
	v_add_u32_e32 v240, 0x1c000, v249
	s_nop 1
	ds_read_b128 v[66:69], v252
	ds_read_b128 v[74:77], v252 offset:1024
	ds_read_b128 v[226:229], v252 offset:2048
	ds_read_b128 v[230:233], v252 offset:3072
	ds_read_b128 v[210:213], v240
	ds_read_b128 v[214:217], v240 offset:1024
	ds_read_b128 v[218:221], v240 offset:2048
	ds_read_b128 v[222:225], v240 offset:3072
	ds_read_b128 v[122:125], v250 offset:32768
	s_waitcnt vmcnt(33)
	ds_read_b128 v[130:133], v250 offset:33792
	ds_read_b128 v[106:109], v250 offset:34816
	ds_read_b128 v[114:117], v250 offset:35840
	ds_read_b128 v[90:93], v250 offset:36864
	ds_read_b128 v[98:101], v250 offset:37888
	ds_read_b128 v[70:73], v250 offset:38912
	ds_read_b128 v[78:81], v250 offset:39936
	s_add_u32 s8, s40, 0x100
	s_addc_u32 s9, s41, 0
	s_mov_b32 m0, s55
	s_nop 0
	global_load_lds_dwordx4 v245, s[8:9]
	s_add_u32 s8, s8, s28
	s_addc_u32 s9, s9, s29
	s_mov_b32 m0, s56
	s_nop 0
	global_load_lds_dwordx4 v245, s[8:9]
	s_and_b64 vcc, exec, s[6:7]
	s_cbranch_vccz .LBB0_216
	s_waitcnt vmcnt(16)
	s_cbranch_execnz .LBB0_199

; #define PG8_STAGE(bufoff, gbase, voff) do { glds_s((const char*)(gbase), (voff), ldsb + (bufoff)); glds_s((const char*)(gbase) + rstep, (voff), ldsb + (bufoff) + 8192u); } while (0)
; #define PG8_LDA(dst, b, h) do { _Pragma("unroll") for (int m = 0; m < 4; ++m) _Pragma("unroll") for (int k = 0; k < 2; ++k) dst[m][k] = *(const LAS bf16x8*)(lds + PG8_SA(b, h) + aoff + m * 2048 + k * 1024); } while (0)
; #define PG8_LDB(dst, b, h) do { _Pragma("unroll") for (int n = 0; n < 2; ++n) _Pragma("unroll") for (int k = 0; k < 2; ++k) dst[n][k] = *(const LAS bf16x8*)(lds + PG8_SB(b, h) + boff + n * 2048 + k * 1024); } while (0)
; #define PG8_MMA(ai, bj, At, Bt) do { __builtin_amdgcn_s_setprio(1); _Pragma("unroll") for (int m = 0; m < 4; ++m) _Pragma("unroll") for (int n = 0; n < 2; ++n) _Pragma("unroll") for (int k = 0; k < 2; ++k) \
;         acc[ai][bj][m][n] = __builtin_amdgcn_mfma_f32_16x16x32_bf16(Bt[n][k], At[m][k], acc[ai][bj][m][n], 0, 0, 0); __builtin_amdgcn_s_setprio(0); } while (0)
; #define PG8_WAIT_V(n) asm volatile("s_waitcnt vmcnt(" #n ")" ::: "memory")
; #define PG8_WAIT_L(n) asm volatile("s_waitcnt lgkmcnt(" #n ")" ::: "memory")
; #define PG8_BAR __builtin_amdgcn_s_barrier()
; #define PG8_SCHED __builtin_amdgcn_sched_barrier(0)
; template <class Epi, class Sched>
; __device__ __forceinline__ void gemm_phase(LAS unsigned char* lds, const Gemm g, const Sched& S, const Epi& E, const int tid) {
;     ...
;             PG8_LDB(B0, 1, 0); PG8_LDB(B1, 1, 1); PG8_SCHED; PG8_LDA(At, 1, 0); PG8_STAGE(PG8_SA(0, 1), a2 + hstep, voffA);
;             if (relax) PG8_WAIT_V(16); else PG8_WAIT_V(8);
;             PG8_WAIT_L(0); PG8_BAR; PG8_MMA(0, 0, At, B0); PG8_MMA(0, 1, At, B1); PG8_BAR; PG8_SCHED;
;             PG8_LDA(At, 1, 1); PG8_STAGE(PG8_SB(1, 0), b3, voffB); PG8_STAGE(PG8_SB(1, 1), b3 + hstep, voffB); PG8_STAGE(PG8_SA(1, 0), a3, voffA);
;             PG8_WAIT_V(8); PG8_WAIT_L(0); PG8_BAR; PG8_MMA(1, 0, At, B0); PG8_MMA(1, 1, At, B1); PG8_BAR; PG8_SCHED;
.LBB0_199:
	s_add_u32 s2, s2, 0x180
	s_waitcnt lgkmcnt(0)
	s_addc_u32 s3, s3, 0
	s_add_u32 s6, s0, 0x180
	s_addc_u32 s7, s1, 0
	s_barrier
	s_setprio 1
	v_mfma_f32_16x16x32_bf16 v[0:3], v[66:69], v[122:125], v[0:3]
	v_mfma_f32_16x16x32_bf16 v[142:145], v[74:77], v[130:133], v[0:3]
	v_mfma_f32_16x16x32_bf16 v[0:3], v[226:229], v[122:125], v[4:7]
	s_waitcnt vmcnt(32)
	v_mfma_f32_16x16x32_bf16 v[134:137], v[230:233], v[130:133], v[0:3]
	v_mfma_f32_16x16x32_bf16 v[0:3], v[66:69], v[106:109], v[8:11]
	v_mfma_f32_16x16x32_bf16 v[126:129], v[74:77], v[114:117], v[0:3]
	v_mfma_f32_16x16x32_bf16 v[0:3], v[226:229], v[106:109], v[12:15]
	v_mfma_f32_16x16x32_bf16 v[118:121], v[230:233], v[114:117], v[0:3]
	v_mfma_f32_16x16x32_bf16 v[0:3], v[66:69], v[90:93], v[16:19]
	v_mfma_f32_16x16x32_bf16 v[110:113], v[74:77], v[98:101], v[0:3]
	v_mfma_f32_16x16x32_bf16 v[0:3], v[226:229], v[90:93], v[20:23]
	v_mfma_f32_16x16x32_bf16 v[102:105], v[230:233], v[98:101], v[0:3]
	v_mfma_f32_16x16x32_bf16 v[0:3], v[66:69], v[70:73], v[24:27]
	v_mfma_f32_16x16x32_bf16 v[94:97], v[74:77], v[78:81], v[0:3]
	v_mfma_f32_16x16x32_bf16 v[0:3], v[226:229], v[70:73], v[28:31]
	v_mfma_f32_16x16x32_bf16 v[82:85], v[230:233], v[78:81], v[0:3]
	v_mfma_f32_16x16x32_bf16 v[0:3], v[210:213], v[122:125], v[32:35]
	v_mfma_f32_16x16x32_bf16 v[146:149], v[214:217], v[130:133], v[0:3]
	v_mfma_f32_16x16x32_bf16 v[0:3], v[218:221], v[122:125], v[36:39]
	v_mfma_f32_16x16x32_bf16 v[138:141], v[222:225], v[130:133], v[0:3]
	v_mfma_f32_16x16x32_bf16 v[0:3], v[210:213], v[106:109], v[40:43]
	v_mfma_f32_16x16x32_bf16 v[130:133], v[214:217], v[114:117], v[0:3]
	v_mfma_f32_16x16x32_bf16 v[0:3], v[218:221], v[106:109], v[44:47]
	v_mfma_f32_16x16x32_bf16 v[122:125], v[222:225], v[114:117], v[0:3]
	v_mfma_f32_16x16x32_bf16 v[0:3], v[210:213], v[90:93], v[48:51]
	v_mfma_f32_16x16x32_bf16 v[114:117], v[214:217], v[98:101], v[0:3]
	v_mfma_f32_16x16x32_bf16 v[0:3], v[218:221], v[90:93], v[52:55]
	v_mfma_f32_16x16x32_bf16 v[106:109], v[222:225], v[98:101], v[0:3]
	v_mfma_f32_16x16x32_bf16 v[0:3], v[210:213], v[70:73], v[56:59]
	v_mfma_f32_16x16x32_bf16 v[98:101], v[214:217], v[78:81], v[0:3]
	v_mfma_f32_16x16x32_bf16 v[0:3], v[218:221], v[70:73], v[60:63]
	v_mfma_f32_16x16x32_bf16 v[90:93], v[222:225], v[78:81], v[0:3]
	s_setprio 0
	s_barrier
	s_nop 4
	ds_read_b128 v[0:3], v250 offset:49152
	ds_read_b128 v[4:7], v250 offset:50176
	ds_read_b128 v[8:11], v250 offset:51200
	ds_read_b128 v[12:15], v250 offset:52224
	ds_read_b128 v[16:19], v250 offset:53248
	ds_read_b128 v[26:29], v250 offset:54272
	ds_read_b128 v[236:239], v250 offset:55296
	ds_read_b128 v[20:23], v250 offset:56320
	s_mov_b32 m0, s59
	s_nop 0
	global_load_lds_dwordx4 v246, s[6:7]
	s_add_u32 s6, s6, s28
	s_addc_u32 s7, s7, s29
	s_mov_b32 m0, s60
	s_nop 0
	global_load_lds_dwordx4 v246, s[6:7]
	s_add_u32 s6, s85, 0x180
	s_addc_u32 s7, s96, 0
	s_mov_b32 m0, s63
	s_nop 0
	global_load_lds_dwordx4 v246, s[6:7]
	s_add_u32 s6, s6, s28
	s_addc_u32 s7, s7, s29
	s_mov_b32 m0, s64
	s_nop 0
	global_load_lds_dwordx4 v246, s[6:7]
	s_mov_b32 m0, s61
	s_nop 0
	global_load_lds_dwordx4 v245, s[2:3]
	s_add_u32 s6, s2, s28
	s_addc_u32 s7, s3, s29
	s_mov_b32 m0, s62
	s_nop 0
	global_load_lds_dwordx4 v245, s[6:7]
	s_waitcnt vmcnt(8)
	s_waitcnt lgkmcnt(0)
	s_barrier
	s_setprio 1
	v_mfma_f32_16x16x32_bf16 v[30:33], v[66:69], v[0:3], v[150:153]
	v_mfma_f32_16x16x32_bf16 v[78:81], v[74:77], v[4:7], v[30:33]
	v_mfma_f32_16x16x32_bf16 v[30:33], v[226:229], v[0:3], v[154:157]
	v_mfma_f32_16x16x32_bf16 v[70:73], v[230:233], v[4:7], v[30:33]
	v_mfma_f32_16x16x32_bf16 v[30:33], v[66:69], v[8:11], v[158:161]
	v_mfma_f32_16x16x32_bf16 v[62:65], v[74:77], v[12:15], v[30:33]
	v_mfma_f32_16x16x32_bf16 v[30:33], v[226:229], v[8:11], v[162:165]
	v_mfma_f32_16x16x32_bf16 v[54:57], v[230:233], v[12:15], v[30:33]
	v_mfma_f32_16x16x32_bf16 v[30:33], v[66:69], v[16:19], v[166:169]
	v_mfma_f32_16x16x32_bf16 v[46:49], v[74:77], v[26:29], v[30:33]
	v_mfma_f32_16x16x32_bf16 v[30:33], v[226:229], v[16:19], v[170:173]
	v_mfma_f32_16x16x32_bf16 v[38:41], v[230:233], v[26:29], v[30:33]
	v_mfma_f32_16x16x32_bf16 v[30:33], v[66:69], v[236:239], v[174:177]
	v_mfma_f32_16x16x32_bf16 v[34:37], v[226:229], v[236:239], v[86:89]
	v_mfma_f32_16x16x32_bf16 v[30:33], v[74:77], v[20:23], v[30:33]
	v_mfma_f32_16x16x32_bf16 v[226:229], v[230:233], v[20:23], v[34:37]
	v_mfma_f32_16x16x32_bf16 v[34:37], v[210:213], v[0:3], v[178:181]
	v_mfma_f32_16x16x32_bf16 v[0:3], v[218:221], v[0:3], v[182:185]
	v_mfma_f32_16x16x32_bf16 v[74:77], v[222:225], v[4:7], v[0:3]
	v_mfma_f32_16x16x32_bf16 v[0:3], v[210:213], v[8:11], v[186:189]
	v_mfma_f32_16x16x32_bf16 v[66:69], v[214:217], v[12:15], v[0:3]
	v_mfma_f32_16x16x32_bf16 v[0:3], v[218:221], v[8:11], v[190:193]
	v_mfma_f32_16x16x32_bf16 v[58:61], v[222:225], v[12:15], v[0:3]
	v_mfma_f32_16x16x32_bf16 v[0:3], v[210:213], v[16:19], v[194:197]
	v_mfma_f32_16x16x32_bf16 v[50:53], v[214:217], v[26:29], v[0:3]
	v_mfma_f32_16x16x32_bf16 v[0:3], v[218:221], v[16:19], v[198:201]
	v_mfma_f32_16x16x32_bf16 v[42:45], v[222:225], v[26:29], v[0:3]
	v_mfma_f32_16x16x32_bf16 v[0:3], v[210:213], v[236:239], v[202:205]
	v_mfma_f32_16x16x32_bf16 v[86:89], v[214:217], v[4:7], v[34:37]
	v_mfma_f32_16x16x32_bf16 v[34:37], v[214:217], v[20:23], v[0:3]
	v_mfma_f32_16x16x32_bf16 v[0:3], v[218:221], v[236:239], v[206:209]
	v_mfma_f32_16x16x32_bf16 v[26:29], v[222:225], v[20:23], v[0:3]
	s_setprio 0
	s_barrier
	s_add_u32 s85, s0, 0x200
	s_addc_u32 s96, s1, 0
	s_mov_b32 s97, 4
; #define PG8_STAGE(bufoff, gbase, voff) do { glds_s((const char*)(gbase), (voff), ldsb + (bufoff)); glds_s((const char*)(gbase) + rstep, (voff), ldsb + (bufoff) + 8192u); } while (0)
; #define PG8_LDA(dst, b, h) do { _Pragma("unroll") for (int m = 0; m < 4; ++m) _Pragma("unroll") for (int k = 0; k < 2; ++k) dst[m][k] = *(const LAS bf16x8*)(lds + PG8_SA(b, h) + aoff + m * 2048 + k * 1024); } while (0)
; #define PG8_LDB(dst, b, h) do { _Pragma("unroll") for (int n = 0; n < 2; ++n) _Pragma("unroll") for (int k = 0; k < 2; ++k) dst[n][k] = *(const LAS bf16x8*)(lds + PG8_SB(b, h) + boff + n * 2048 + k * 1024); } while (0)
; #define PG8_MMA(ai, bj, At, Bt) do { __builtin_amdgcn_s_setprio(1); _Pragma("unroll") for (int m = 0; m < 4; ++m) _Pragma("unroll") for (int n = 0; n < 2; ++n) _Pragma("unroll") for (int k = 0; k < 2; ++k) \
;         acc[ai][bj][m][n] = __builtin_amdgcn_mfma_f32_16x16x32_bf16(Bt[n][k], At[m][k], acc[ai][bj][m][n], 0, 0, 0); __builtin_amdgcn_s_setprio(0); } while (0)
; #define PG8_WAIT_V(n) asm volatile("s_waitcnt vmcnt(" #n ")" ::: "memory")
; #define PG8_WAIT_L(n) asm volatile("s_waitcnt lgkmcnt(" #n ")" ::: "memory")
; #define PG8_BAR __builtin_amdgcn_s_barrier()
; template <class Epi, class Sched>
; __device__ __forceinline__ void gemm_phase(LAS unsigned char* lds, const Gemm g, const Sched& S, const Epi& E, const int tid) {
;     ...
;         for (int t = 0; t < nt; t += 2) {
;             const bool last = (t == nt - 2);
;             const char* a1 = cA + (size_t)(t + 1) * kstep;
;             const char* a2 = last ? nA : cA + (size_t)(t + 2) * kstep; const char* b2 = last ? nB : cB + (size_t)(t + 2) * kstep;
;             const char* a3 = a2 + kstep; const char* b3 = b2 + kstep;
;             const bool relax = (t == 0) && (ui > 0);
;             PG8_LDB(B0, 0, 0); PG8_LDB(B1, 0, 1); PG8_SCHED; PG8_LDA(At, 0, 0); if (!relax) PG8_STAGE(PG8_SA(1, 1), a1 + hstep, voffA);
;             if (relax) PG8_WAIT_V(16); else PG8_WAIT_V(8);
;             PG8_WAIT_L(0); PG8_BAR; PG8_MMA(0, 0, At, B0); PG8_MMA(0, 1, At, B1); PG8_BAR; PG8_SCHED;
;             PG8_LDA(At, 0, 1); PG8_STAGE(PG8_SB(0, 0), b2, voffB); PG8_STAGE(PG8_SB(0, 1), b2 + hstep, voffB); PG8_STAGE(PG8_SA(0, 0), a2, voffA);
;             if (relax) PG8_WAIT_V(16); else PG8_WAIT_V(8);
;             PG8_WAIT_L(0); PG8_BAR; PG8_MMA(1, 0, At, B0); PG8_MMA(1, 1, At, B1); PG8_BAR; PG8_SCHED;
.LBB0_200:
	s_add_u32 s0, s2, 0x80
	s_nop 0
	ds_read_b128 v[0:3], v234
	ds_read_b128 v[4:7], v234 offset:1024
	ds_read_b128 v[8:11], v234 offset:2048
	ds_read_b128 v[12:15], v234 offset:3072
	ds_read_b128 v[16:19], v251
	ds_read_b128 v[20:23], v251 offset:1024
	ds_read_b128 v[150:153], v251 offset:2048
	ds_read_b128 v[154:157], v251 offset:3072
	s_addc_u32 s1, s3, 0
	s_cmp_eq_u32 s42, s97
	s_cselect_b32 s8, s80, s0
	s_cselect_b32 s9, s81, s1
	s_cselect_b32 s40, s82, s85
	s_cselect_b32 s41, s83, s96
	s_add_u32 s0, s8, 0x80
	s_addc_u32 s1, s9, 0
	s_add_u32 s6, s40, 0x80
	s_addc_u32 s7, s41, 0
	ds_read_b128 v[158:161], v250
	ds_read_b128 v[162:165], v250 offset:1024
	ds_read_b128 v[166:169], v250 offset:2048
	ds_read_b128 v[170:173], v250 offset:3072
	ds_read_b128 v[174:177], v250 offset:4096
	ds_read_b128 v[178:181], v250 offset:5120
	ds_read_b128 v[182:185], v250 offset:6144
	ds_read_b128 v[186:189], v250 offset:7168
	s_add_u32 s44, s2, s30
	s_addc_u32 s45, s3, s31
	s_mov_b32 m0, s65
	s_nop 0
	global_load_lds_dwordx4 v245, s[44:45]
	s_add_u32 s44, s44, s28
	s_addc_u32 s45, s45, s29
	s_mov_b32 m0, s86
	s_nop 0
	global_load_lds_dwordx4 v245, s[44:45]
	s_waitcnt vmcnt(8)
	s_waitcnt lgkmcnt(0)
	s_barrier
	s_setprio 1
	v_mfma_f32_16x16x32_bf16 v[142:145], v[0:3], v[158:161], v[142:145]
	v_mfma_f32_16x16x32_bf16 v[134:137], v[8:11], v[158:161], v[134:137]
	v_mfma_f32_16x16x32_bf16 v[126:129], v[0:3], v[166:169], v[126:129]
	v_mfma_f32_16x16x32_bf16 v[118:121], v[8:11], v[166:169], v[118:121]
	v_mfma_f32_16x16x32_bf16 v[110:113], v[0:3], v[174:177], v[110:113]
	v_mfma_f32_16x16x32_bf16 v[102:105], v[8:11], v[174:177], v[102:105]
	v_mfma_f32_16x16x32_bf16 v[94:97], v[0:3], v[182:185], v[94:97]
	v_mfma_f32_16x16x32_bf16 v[82:85], v[8:11], v[182:185], v[82:85]
	v_mfma_f32_16x16x32_bf16 v[142:145], v[4:7], v[162:165], v[142:145]
	v_mfma_f32_16x16x32_bf16 v[134:137], v[12:15], v[162:165], v[134:137]
	v_mfma_f32_16x16x32_bf16 v[126:129], v[4:7], v[170:173], v[126:129]
	v_mfma_f32_16x16x32_bf16 v[118:121], v[12:15], v[170:173], v[118:121]
	v_mfma_f32_16x16x32_bf16 v[110:113], v[4:7], v[178:181], v[110:113]
	v_mfma_f32_16x16x32_bf16 v[102:105], v[12:15], v[178:181], v[102:105]
	v_mfma_f32_16x16x32_bf16 v[94:97], v[4:7], v[186:189], v[94:97]
	v_mfma_f32_16x16x32_bf16 v[82:85], v[12:15], v[186:189], v[82:85]
	v_mfma_f32_16x16x32_bf16 v[146:149], v[16:19], v[158:161], v[146:149]
	v_mfma_f32_16x16x32_bf16 v[138:141], v[150:153], v[158:161], v[138:141]
	v_mfma_f32_16x16x32_bf16 v[130:133], v[16:19], v[166:169], v[130:133]
	v_mfma_f32_16x16x32_bf16 v[122:125], v[150:153], v[166:169], v[122:125]
	v_mfma_f32_16x16x32_bf16 v[114:117], v[16:19], v[174:177], v[114:117]
	v_mfma_f32_16x16x32_bf16 v[106:109], v[150:153], v[174:177], v[106:109]
	v_mfma_f32_16x16x32_bf16 v[98:101], v[16:19], v[182:185], v[98:101]
	v_mfma_f32_16x16x32_bf16 v[90:93], v[150:153], v[182:185], v[90:93]
	v_mfma_f32_16x16x32_bf16 v[146:149], v[20:23], v[162:165], v[146:149]
	v_mfma_f32_16x16x32_bf16 v[138:141], v[154:157], v[162:165], v[138:141]
	v_mfma_f32_16x16x32_bf16 v[130:133], v[20:23], v[170:173], v[130:133]
	v_mfma_f32_16x16x32_bf16 v[122:125], v[154:157], v[170:173], v[122:125]
	v_mfma_f32_16x16x32_bf16 v[114:117], v[20:23], v[178:181], v[114:117]
	v_mfma_f32_16x16x32_bf16 v[106:109], v[154:157], v[178:181], v[106:109]
	v_mfma_f32_16x16x32_bf16 v[98:101], v[20:23], v[186:189], v[98:101]
	v_mfma_f32_16x16x32_bf16 v[90:93], v[154:157], v[186:189], v[90:93]
	s_setprio 0
	s_barrier
	s_add_u32 s44, s40, s28
	ds_read_b128 v[158:161], v250 offset:16384
	ds_read_b128 v[162:165], v250 offset:17408
	ds_read_b128 v[166:169], v250 offset:18432
	ds_read_b128 v[170:173], v250 offset:19456
	ds_read_b128 v[174:177], v250 offset:20480
	ds_read_b128 v[178:181], v250 offset:21504
	ds_read_b128 v[182:185], v250 offset:22528
	ds_read_b128 v[186:189], v250 offset:23552
	s_addc_u32 s45, s41, s29
	s_mov_b32 m0, s50
	s_nop 0
	global_load_lds_dwordx4 v246, s[40:41]
	s_add_u32 s40, s40, s30
	s_mov_b32 m0, s51
	s_nop 0
	global_load_lds_dwordx4 v246, s[44:45]
	s_addc_u32 s41, s41, s31
	s_mov_b32 m0, s52
	s_nop 0
	global_load_lds_dwordx4 v246, s[40:41]
	s_add_u32 s44, s40, s28
	s_addc_u32 s45, s41, s29
	s_mov_b32 m0, s53
	s_nop 0
	global_load_lds_dwordx4 v246, s[44:45]
	s_add_u32 s44, s8, s28
	s_mov_b32 m0, s49
	s_nop 0
	global_load_lds_dwordx4 v245, s[8:9]
	s_addc_u32 s45, s9, s29
	s_mov_b32 m0, s54
	s_nop 0
	global_load_lds_dwordx4 v245, s[44:45]
	s_waitcnt vmcnt(8)
	s_waitcnt lgkmcnt(0)
	s_barrier
	s_setprio 1
	v_mfma_f32_16x16x32_bf16 v[78:81], v[0:3], v[158:161], v[78:81]
	v_mfma_f32_16x16x32_bf16 v[70:73], v[8:11], v[158:161], v[70:73]
	v_mfma_f32_16x16x32_bf16 v[62:65], v[0:3], v[166:169], v[62:65]
	v_mfma_f32_16x16x32_bf16 v[54:57], v[8:11], v[166:169], v[54:57]
	v_mfma_f32_16x16x32_bf16 v[46:49], v[0:3], v[174:177], v[46:49]
	v_mfma_f32_16x16x32_bf16 v[38:41], v[8:11], v[174:177], v[38:41]
	v_mfma_f32_16x16x32_bf16 v[0:3], v[0:3], v[182:185], v[30:33]
	v_mfma_f32_16x16x32_bf16 v[78:81], v[4:7], v[162:165], v[78:81]
	v_mfma_f32_16x16x32_bf16 v[70:73], v[12:15], v[162:165], v[70:73]
	v_mfma_f32_16x16x32_bf16 v[62:65], v[4:7], v[170:173], v[62:65]
	v_mfma_f32_16x16x32_bf16 v[54:57], v[12:15], v[170:173], v[54:57]
	v_mfma_f32_16x16x32_bf16 v[46:49], v[4:7], v[178:181], v[46:49]
	v_mfma_f32_16x16x32_bf16 v[38:41], v[12:15], v[178:181], v[38:41]
	v_mfma_f32_16x16x32_bf16 v[0:3], v[4:7], v[186:189], v[0:3]
	v_mfma_f32_16x16x32_bf16 v[4:7], v[8:11], v[182:185], v[226:229]
	v_mfma_f32_16x16x32_bf16 v[4:7], v[12:15], v[186:189], v[4:7]
	v_mfma_f32_16x16x32_bf16 v[30:33], v[16:19], v[166:169], v[66:69]
	v_mfma_f32_16x16x32_bf16 v[66:69], v[20:23], v[170:173], v[30:33]
	v_mfma_f32_16x16x32_bf16 v[30:33], v[150:153], v[166:169], v[58:61]
	v_mfma_f32_16x16x32_bf16 v[58:61], v[154:157], v[170:173], v[30:33]
	v_mfma_f32_16x16x32_bf16 v[30:33], v[16:19], v[174:177], v[50:53]
	v_mfma_f32_16x16x32_bf16 v[8:11], v[16:19], v[158:161], v[86:89]
	v_mfma_f32_16x16x32_bf16 v[50:53], v[20:23], v[178:181], v[30:33]
	v_mfma_f32_16x16x32_bf16 v[30:33], v[150:153], v[174:177], v[42:45]
	v_mfma_f32_16x16x32_bf16 v[16:19], v[16:19], v[182:185], v[34:37]
	v_mfma_f32_16x16x32_bf16 v[8:11], v[20:23], v[162:165], v[8:11]
	v_mfma_f32_16x16x32_bf16 v[12:15], v[150:153], v[158:161], v[74:77]
	v_mfma_f32_16x16x32_bf16 v[42:45], v[154:157], v[178:181], v[30:33]
	v_mfma_f32_16x16x32_bf16 v[16:19], v[20:23], v[186:189], v[16:19]
	v_mfma_f32_16x16x32_bf16 v[20:23], v[150:153], v[182:185], v[26:29]
	v_mfma_f32_16x16x32_bf16 v[12:15], v[154:157], v[162:165], v[12:15]
	v_mfma_f32_16x16x32_bf16 v[20:23], v[154:157], v[186:189], v[20:23]
	s_setprio 0
	s_barrier
; #define PG8_STAGE(bufoff, gbase, voff) do { glds_s((const char*)(gbase), (voff), ldsb + (bufoff)); glds_s((const char*)(gbase) + rstep, (voff), ldsb + (bufoff) + 8192u); } while (0)
; #define PG8_LDA(dst, b, h) do { _Pragma("unroll") for (int m = 0; m < 4; ++m) _Pragma("unroll") for (int k = 0; k < 2; ++k) dst[m][k] = *(const LAS bf16x8*)(lds + PG8_SA(b, h) + aoff + m * 2048 + k * 1024); } while (0)
; #define PG8_LDB(dst, b, h) do { _Pragma("unroll") for (int n = 0; n < 2; ++n) _Pragma("unroll") for (int k = 0; k < 2; ++k) dst[n][k] = *(const LAS bf16x8*)(lds + PG8_SB(b, h) + boff + n * 2048 + k * 1024); } while (0)
; #define PG8_MMA(ai, bj, At, Bt) do { __builtin_amdgcn_s_setprio(1); _Pragma("unroll") for (int m = 0; m < 4; ++m) _Pragma("unroll") for (int n = 0; n < 2; ++n) _Pragma("unroll") for (int k = 0; k < 2; ++k) \
;         acc[ai][bj][m][n] = __builtin_amdgcn_mfma_f32_16x16x32_bf16(Bt[n][k], At[m][k], acc[ai][bj][m][n], 0, 0, 0); __builtin_amdgcn_s_setprio(0); } while (0)
; #define PG8_WAIT_V(n) asm volatile("s_waitcnt vmcnt(" #n ")" ::: "memory")
; #define PG8_WAIT_L(n) asm volatile("s_waitcnt lgkmcnt(" #n ")" ::: "memory")
; #define PG8_BAR __builtin_amdgcn_s_barrier()
; #define PG8_SCHED __builtin_amdgcn_sched_barrier(0)
; template <class Epi, class Sched>
; __device__ __forceinline__ void gemm_phase(LAS unsigned char* lds, const Gemm g, const Sched& S, const Epi& E, const int tid) {
;     ...
;             PG8_LDB(B0, 1, 0); PG8_LDB(B1, 1, 1); PG8_SCHED; PG8_LDA(At, 1, 0); PG8_STAGE(PG8_SA(0, 1), a2 + hstep, voffA);
;             if (relax) PG8_WAIT_V(16); else PG8_WAIT_V(8);
;             PG8_WAIT_L(0); PG8_BAR; PG8_MMA(0, 0, At, B0); PG8_MMA(0, 1, At, B1); PG8_BAR; PG8_SCHED;
;             PG8_LDA(At, 1, 1); PG8_STAGE(PG8_SB(1, 0), b3, voffB); PG8_STAGE(PG8_SB(1, 1), b3 + hstep, voffB); PG8_STAGE(PG8_SA(1, 0), a3, voffA);
;             PG8_WAIT_V(8); PG8_WAIT_L(0); PG8_BAR; PG8_MMA(1, 0, At, B0); PG8_MMA(1, 1, At, B1); PG8_BAR; PG8_SCHED;
;         }
	ds_read_b128 v[24:27], v252
	ds_read_b128 v[28:31], v252 offset:1024
	ds_read_b128 v[34:37], v252 offset:2048
	ds_read_b128 v[74:77], v252 offset:3072
	ds_read_b128 v[150:153], v240
	ds_read_b128 v[154:157], v240 offset:1024
	ds_read_b128 v[158:161], v240 offset:2048
	ds_read_b128 v[162:165], v240 offset:3072
	ds_read_b128 v[86:89], v250 offset:32768
	ds_read_b128 v[166:169], v250 offset:33792
	ds_read_b128 v[170:173], v250 offset:34816
	ds_read_b128 v[174:177], v250 offset:35840
	ds_read_b128 v[178:181], v250 offset:36864
	ds_read_b128 v[182:185], v250 offset:37888
	ds_read_b128 v[186:189], v250 offset:38912
	ds_read_b128 v[190:193], v250 offset:39936
	s_add_u32 s8, s8, s30
	s_addc_u32 s9, s9, s31
	s_mov_b32 m0, s55
	s_nop 0
	global_load_lds_dwordx4 v245, s[8:9]
	s_add_u32 s8, s8, s28
	s_addc_u32 s9, s9, s29
	s_mov_b32 m0, s56
	s_nop 0
	global_load_lds_dwordx4 v245, s[8:9]
	s_waitcnt vmcnt(8)
	s_waitcnt lgkmcnt(0)
	s_barrier
	s_setprio 1
	v_mfma_f32_16x16x32_bf16 v[142:145], v[24:27], v[86:89], v[142:145]
	v_mfma_f32_16x16x32_bf16 v[134:137], v[34:37], v[86:89], v[134:137]
	v_mfma_f32_16x16x32_bf16 v[126:129], v[24:27], v[170:173], v[126:129]
	v_mfma_f32_16x16x32_bf16 v[118:121], v[34:37], v[170:173], v[118:121]
	v_mfma_f32_16x16x32_bf16 v[110:113], v[24:27], v[178:181], v[110:113]
	v_mfma_f32_16x16x32_bf16 v[102:105], v[34:37], v[178:181], v[102:105]
	v_mfma_f32_16x16x32_bf16 v[94:97], v[24:27], v[186:189], v[94:97]
	v_mfma_f32_16x16x32_bf16 v[82:85], v[34:37], v[186:189], v[82:85]
	v_mfma_f32_16x16x32_bf16 v[142:145], v[28:31], v[166:169], v[142:145]
	v_mfma_f32_16x16x32_bf16 v[134:137], v[74:77], v[166:169], v[134:137]
	v_mfma_f32_16x16x32_bf16 v[126:129], v[28:31], v[174:177], v[126:129]
	v_mfma_f32_16x16x32_bf16 v[118:121], v[74:77], v[174:177], v[118:121]
	v_mfma_f32_16x16x32_bf16 v[110:113], v[28:31], v[182:185], v[110:113]
	v_mfma_f32_16x16x32_bf16 v[102:105], v[74:77], v[182:185], v[102:105]
	v_mfma_f32_16x16x32_bf16 v[94:97], v[28:31], v[190:193], v[94:97]
	v_mfma_f32_16x16x32_bf16 v[82:85], v[74:77], v[190:193], v[82:85]
	v_mfma_f32_16x16x32_bf16 v[146:149], v[150:153], v[86:89], v[146:149]
	v_mfma_f32_16x16x32_bf16 v[86:89], v[158:161], v[86:89], v[138:141]
	v_mfma_f32_16x16x32_bf16 v[138:141], v[162:165], v[166:169], v[86:89]
	v_mfma_f32_16x16x32_bf16 v[86:89], v[150:153], v[170:173], v[130:133]
	v_mfma_f32_16x16x32_bf16 v[130:133], v[154:157], v[174:177], v[86:89]
	v_mfma_f32_16x16x32_bf16 v[86:89], v[158:161], v[170:173], v[122:125]
	v_mfma_f32_16x16x32_bf16 v[122:125], v[162:165], v[174:177], v[86:89]
	v_mfma_f32_16x16x32_bf16 v[86:89], v[150:153], v[178:181], v[114:117]
	v_mfma_f32_16x16x32_bf16 v[114:117], v[154:157], v[182:185], v[86:89]
	v_mfma_f32_16x16x32_bf16 v[86:89], v[158:161], v[178:181], v[106:109]
	v_mfma_f32_16x16x32_bf16 v[106:109], v[162:165], v[182:185], v[86:89]
	v_mfma_f32_16x16x32_bf16 v[86:89], v[150:153], v[186:189], v[98:101]
	v_mfma_f32_16x16x32_bf16 v[98:101], v[154:157], v[190:193], v[86:89]
	v_mfma_f32_16x16x32_bf16 v[86:89], v[158:161], v[186:189], v[90:93]
	v_mfma_f32_16x16x32_bf16 v[146:149], v[154:157], v[166:169], v[146:149]
	v_mfma_f32_16x16x32_bf16 v[90:93], v[162:165], v[190:193], v[86:89]
	s_setprio 0
	s_barrier
	ds_read_b128 v[166:169], v250 offset:49152
	ds_read_b128 v[170:173], v250 offset:50176
	ds_read_b128 v[174:177], v250 offset:51200
	ds_read_b128 v[178:181], v250 offset:52224
	ds_read_b128 v[182:185], v250 offset:53248
	ds_read_b128 v[186:189], v250 offset:54272
	ds_read_b128 v[190:193], v250 offset:55296
	ds_read_b128 v[194:197], v250 offset:56320
	s_mov_b32 m0, s59
	s_nop 0
	global_load_lds_dwordx4 v246, s[6:7]
	s_add_u32 s6, s6, s28
	s_addc_u32 s7, s7, s29
	s_mov_b32 m0, s60
	s_nop 0
	global_load_lds_dwordx4 v246, s[6:7]
	s_add_u32 s6, s40, 0x80
	s_addc_u32 s7, s41, 0
	s_mov_b32 m0, s63
	s_nop 0
	global_load_lds_dwordx4 v246, s[6:7]
	s_add_u32 s6, s6, s28
	s_addc_u32 s7, s7, s29
	s_mov_b32 m0, s64
	s_nop 0
	global_load_lds_dwordx4 v246, s[6:7]
	s_mov_b32 m0, s61
	s_nop 0
	global_load_lds_dwordx4 v245, s[0:1]
	s_add_u32 s0, s0, s28
	s_addc_u32 s1, s1, s29
	s_mov_b32 m0, s62
	s_nop 0
	global_load_lds_dwordx4 v245, s[0:1]
	s_waitcnt vmcnt(8)
	s_waitcnt lgkmcnt(0)
	s_barrier
	s_setprio 1
	v_mfma_f32_16x16x32_bf16 v[78:81], v[24:27], v[166:169], v[78:81]
	v_mfma_f32_16x16x32_bf16 v[62:65], v[24:27], v[174:177], v[62:65]
	v_mfma_f32_16x16x32_bf16 v[46:49], v[24:27], v[182:185], v[46:49]
	v_mfma_f32_16x16x32_bf16 v[0:3], v[24:27], v[190:193], v[0:3]
	v_mfma_f32_16x16x32_bf16 v[78:81], v[28:31], v[170:173], v[78:81]
	v_mfma_f32_16x16x32_bf16 v[70:73], v[34:37], v[166:169], v[70:73]
	v_mfma_f32_16x16x32_bf16 v[62:65], v[28:31], v[178:181], v[62:65]
	v_mfma_f32_16x16x32_bf16 v[54:57], v[34:37], v[174:177], v[54:57]
	v_mfma_f32_16x16x32_bf16 v[46:49], v[28:31], v[186:189], v[46:49]
	v_mfma_f32_16x16x32_bf16 v[38:41], v[34:37], v[182:185], v[38:41]
	v_mfma_f32_16x16x32_bf16 v[30:33], v[28:31], v[194:197], v[0:3]
	v_mfma_f32_16x16x32_bf16 v[0:3], v[34:37], v[190:193], v[4:7]
	v_mfma_f32_16x16x32_bf16 v[70:73], v[74:77], v[170:173], v[70:73]
	v_mfma_f32_16x16x32_bf16 v[54:57], v[74:77], v[178:181], v[54:57]
	v_mfma_f32_16x16x32_bf16 v[38:41], v[74:77], v[186:189], v[38:41]
	v_mfma_f32_16x16x32_bf16 v[226:229], v[74:77], v[194:197], v[0:3]
	v_mfma_f32_16x16x32_bf16 v[0:3], v[150:153], v[166:169], v[8:11]
	v_mfma_f32_16x16x32_bf16 v[86:89], v[154:157], v[170:173], v[0:3]
	v_mfma_f32_16x16x32_bf16 v[0:3], v[158:161], v[166:169], v[12:15]
	v_mfma_f32_16x16x32_bf16 v[74:77], v[162:165], v[170:173], v[0:3]
	v_mfma_f32_16x16x32_bf16 v[0:3], v[150:153], v[174:177], v[66:69]
	v_mfma_f32_16x16x32_bf16 v[66:69], v[154:157], v[178:181], v[0:3]
	v_mfma_f32_16x16x32_bf16 v[0:3], v[158:161], v[174:177], v[58:61]
	v_mfma_f32_16x16x32_bf16 v[58:61], v[162:165], v[178:181], v[0:3]
	v_mfma_f32_16x16x32_bf16 v[0:3], v[150:153], v[182:185], v[50:53]
	v_mfma_f32_16x16x32_bf16 v[50:53], v[154:157], v[186:189], v[0:3]
	v_mfma_f32_16x16x32_bf16 v[0:3], v[158:161], v[182:185], v[42:45]
	v_mfma_f32_16x16x32_bf16 v[42:45], v[162:165], v[186:189], v[0:3]
	v_mfma_f32_16x16x32_bf16 v[0:3], v[150:153], v[190:193], v[16:19]
	v_mfma_f32_16x16x32_bf16 v[34:37], v[154:157], v[194:197], v[0:3]
	v_mfma_f32_16x16x32_bf16 v[0:3], v[158:161], v[190:193], v[20:23]
	v_mfma_f32_16x16x32_bf16 v[26:29], v[162:165], v[194:197], v[0:3]
	s_setprio 0
	s_barrier
	s_add_u32 s2, s2, 0x100
	s_addc_u32 s3, s3, 0
	s_add_i32 s0, s97, 2
	s_add_u32 s85, s85, 0x100
	s_addc_u32 s96, s96, 0
	s_cmp_ge_u32 s97, s42
	s_mov_b32 s97, s0
	s_cbranch_scc0 .LBB0_200
	s_and_b64 vcc, exec, s[68:69]
	s_cbranch_vccz .LBB0_203
	s_barrier
